# v18 + in-proj rotary epilogue: cos/sin rows of all 8 blocks prefetched up front (global loads/stores, counted vmcnt)
# speedup vs baseline: 1.0220x; 1.0032x over previous
.LBB0_143:
	s_add_i32 s0, s55, -12
	s_cmp_lt_u32 s0, 6
	v_lshl_add_u32 v170, s56, 8, v166
	v_mov_b32_e32 v160, 1.0
	v_mov_b32_e32 v161, 0
	s_cselect_b64 s[10:11], -1, 0
	s_cmp_gt_u32 s0, 5
	v_mov_b32_e32 v165, 0
	v_mov_b32_e32 v131, 0
	v_mov_b32_e32 v163, 0
	v_mov_b32_e32 v133, 0
	v_mov_b32_e32 v164, 1.0
	v_mov_b32_e32 v130, 1.0
	v_mov_b32_e32 v162, 1.0
	v_mov_b32_e32 v132, 1.0
	s_cbranch_scc1 .LBB0_145
	v_mov_b32_e32 v245, 0
	v_lshlrev_b32_e32 v244, 8, v170
	v_and_b32_e32 v244, 0x7ff00, v244
	v_lshl_add_u64 v[246:247], v[142:143], 0, v[244:245]
	global_load_dwordx4 v[184:187], v[246:247], off
	v_lshl_add_u64 v[246:247], v[144:145], 0, v[244:245]
	global_load_dwordx4 v[188:191], v[246:247], off
	v_add_u32_e32 v244, 16, v170
	v_lshlrev_b32_e32 v244, 8, v244
	v_and_b32_e32 v244, 0x7ff00, v244
	v_lshl_add_u64 v[246:247], v[142:143], 0, v[244:245]
	global_load_dwordx4 v[192:195], v[246:247], off
	v_lshl_add_u64 v[246:247], v[144:145], 0, v[244:245]
	global_load_dwordx4 v[196:199], v[246:247], off
	v_add_u32_e32 v244, 32, v170
	v_lshlrev_b32_e32 v244, 8, v244
	v_and_b32_e32 v244, 0x7ff00, v244
	v_lshl_add_u64 v[246:247], v[142:143], 0, v[244:245]
	global_load_dwordx4 v[200:203], v[246:247], off
	v_lshl_add_u64 v[246:247], v[144:145], 0, v[244:245]
	global_load_dwordx4 v[216:219], v[246:247], off
	v_add_u32_e32 v244, 48, v170
	v_lshlrev_b32_e32 v244, 8, v244
	v_and_b32_e32 v244, 0x7ff00, v244
	v_lshl_add_u64 v[246:247], v[142:143], 0, v[244:245]
	global_load_dwordx4 v[220:223], v[246:247], off
	v_lshl_add_u64 v[246:247], v[144:145], 0, v[244:245]
	global_load_dwordx4 v[224:227], v[246:247], off
	v_add_u32_e32 v244, 0x80, v170
	v_lshlrev_b32_e32 v244, 8, v244
	v_and_b32_e32 v244, 0x7ff00, v244
	v_lshl_add_u64 v[246:247], v[142:143], 0, v[244:245]
	global_load_dwordx4 v[228:231], v[246:247], off
	v_lshl_add_u64 v[246:247], v[144:145], 0, v[244:245]
	global_load_dwordx4 v[232:235], v[246:247], off
	v_add_u32_e32 v244, 0x90, v170
	v_lshlrev_b32_e32 v244, 8, v244
	v_and_b32_e32 v244, 0x7ff00, v244
	v_lshl_add_u64 v[246:247], v[142:143], 0, v[244:245]
	global_load_dwordx4 v[236:239], v[246:247], off
	v_lshl_add_u64 v[246:247], v[144:145], 0, v[244:245]
	global_load_dwordx4 v[240:243], v[246:247], off
	s_waitcnt vmcnt(10)
	v_mov_b32_e32 v130, v184
	v_mov_b32_e32 v131, v185
	v_mov_b32_e32 v132, v186
	v_mov_b32_e32 v133, v187
	v_mov_b32_e32 v172, v188
	v_mov_b32_e32 v173, v189
	v_mov_b32_e32 v174, v190
	v_mov_b32_e32 v175, v191
	v_mov_b32_e32 v165, v130
	v_mov_b32_e32 v163, v132
	v_mov_b32_e32 v164, v172
	v_mov_b32_e32 v130, v173
	v_mov_b32_e32 v162, v174
	v_mov_b32_e32 v132, v175
.LBB0_145:
	v_pk_mul_f32 v[174:175], v[126:127], v[164:165]
	v_lshl_or_b32 v158, s55, 8, v168
	v_sub_f32_e32 v0, v174, v175
	v_mov_b32_e32 v174, v165
	v_mov_b32_e32 v175, v164
	v_pk_mul_f32 v[126:127], v[126:127], v[174:175]
	v_mov_b64_e32 v[172:173], s[12:13]
	v_add_f32_e32 v171, v126, v127
	v_pk_mul_f32 v[126:127], v[128:129], v[130:131]
	v_mov_b32_e32 v176, v133
	v_sub_f32_e32 v178, v126, v127
	v_mov_b32_e32 v126, v131
	v_mov_b32_e32 v127, v130
	v_pk_mul_f32 v[128:129], v[128:129], v[126:127]
	v_mov_b32_e32 v177, v132
	v_add_f32_e32 v179, v128, v129
	v_pk_mul_f32 v[128:129], v[122:123], v[162:163]
	v_ashrrev_i32_e32 v159, 31, v158
	v_sub_f32_e32 v180, v128, v129
	v_mov_b32_e32 v128, v163
	v_mov_b32_e32 v129, v162
	v_pk_mul_f32 v[122:123], v[122:123], v[128:129]
	v_mad_i64_i32 v[172:173], s[0:1], v170, s43, v[172:173]
	v_add_f32_e32 v181, v122, v123
	v_pk_mul_f32 v[122:123], v[124:125], v[132:133]
	v_lshl_add_u64 v[172:173], v[158:159], 1, v[172:173]
	v_sub_f32_e32 v182, v122, v123
	v_pk_mul_f32 v[122:123], v[124:125], v[176:177]
	s_nop 0
	v_add_f32_e32 v125, v122, v123
	v_cvt_pk_bf16_f32 v122, v0, v171
	v_cvt_pk_bf16_f32 v123, v178, v179
	v_cvt_pk_bf16_f32 v124, v180, v181
	v_cvt_pk_bf16_f32 v125, v182, v125
	global_store_dwordx4 v[172:173], v[122:125], off
	s_nop 1
	v_pk_mul_f32 v[122:123], v[118:119], v[164:165]
	v_pk_mul_f32 v[118:119], v[118:119], v[174:175]
	v_sub_f32_e32 v0, v122, v123
	v_add_f32_e32 v122, v118, v119
	v_pk_mul_f32 v[118:119], v[120:121], v[130:131]
	s_nop 0
	v_sub_f32_e32 v123, v118, v119
	v_pk_mul_f32 v[118:119], v[120:121], v[126:127]
	s_nop 0
	v_add_f32_e32 v120, v118, v119
	v_pk_mul_f32 v[118:119], v[114:115], v[162:163]
	v_pk_mul_f32 v[114:115], v[114:115], v[128:129]
	v_sub_f32_e32 v118, v118, v119
	v_add_f32_e32 v119, v114, v115
	v_pk_mul_f32 v[114:115], v[116:117], v[132:133]
	s_nop 0
	v_sub_f32_e32 v121, v114, v115
	v_pk_mul_f32 v[114:115], v[116:117], v[176:177]
	s_nop 0
	v_add_f32_e32 v117, v114, v115
	v_cvt_pk_bf16_f32 v114, v0, v122
	v_cvt_pk_bf16_f32 v115, v123, v120
	v_cvt_pk_bf16_f32 v116, v118, v119
	v_cvt_pk_bf16_f32 v117, v121, v117
	global_store_dwordx4 v[172:173], v[114:117], off offset:256
	v_cndmask_b32_e64 v0, 0, 1, s[10:11]
	v_or_b32_e32 v120, 16, v170
	v_cmp_ne_u32_e64 s[8:9], 1, v0
	s_andn2_b64 vcc, exec, s[10:11]
	v_mov_b32_e32 v115, 0
	v_mov_b32_e32 v119, 0
	v_mov_b32_e32 v117, 0
	v_mov_b32_e32 v114, 1.0
	v_mov_b32_e32 v118, 1.0
	v_mov_b32_e32 v116, 1.0
	s_cbranch_vccnz .LBB0_147
	s_waitcnt vmcnt(10)
	v_mov_b32_e32 v114, v192
	v_mov_b32_e32 v115, v193
	v_mov_b32_e32 v116, v194
	v_mov_b32_e32 v117, v195
	v_mov_b32_e32 v122, v196
	v_mov_b32_e32 v123, v197
	v_mov_b32_e32 v124, v198
	v_mov_b32_e32 v125, v199
	v_mov_b32_e32 v161, v114
	v_mov_b32_e32 v119, v116
	v_mov_b32_e32 v160, v122
	v_mov_b32_e32 v114, v123
	v_mov_b32_e32 v118, v124
	v_mov_b32_e32 v116, v125
.LBB0_147:
	v_mov_b64_e32 v[122:123], s[12:13]
	v_mad_i64_i32 v[120:121], s[0:1], v120, s43, v[122:123]
	v_pk_mul_f32 v[122:123], v[110:111], v[160:161]
	v_mov_b32_e32 v124, v117
	v_sub_f32_e32 v0, v122, v123
	v_mov_b32_e32 v122, v161
	v_mov_b32_e32 v123, v160
	v_pk_mul_f32 v[110:111], v[110:111], v[122:123]
	v_mov_b32_e32 v125, v116
	v_add_f32_e32 v126, v110, v111
	v_pk_mul_f32 v[110:111], v[112:113], v[114:115]
	v_lshl_add_u64 v[120:121], v[158:159], 1, v[120:121]
	v_sub_f32_e32 v127, v110, v111
	v_mov_b32_e32 v110, v115
	v_mov_b32_e32 v111, v114
	v_pk_mul_f32 v[112:113], v[112:113], v[110:111]
	s_nop 0
	v_add_f32_e32 v128, v112, v113
	v_pk_mul_f32 v[112:113], v[106:107], v[118:119]
	s_nop 0
	v_sub_f32_e32 v129, v112, v113
	v_mov_b32_e32 v112, v119
	v_mov_b32_e32 v113, v118
	v_pk_mul_f32 v[106:107], v[106:107], v[112:113]
	s_nop 0
	v_add_f32_e32 v130, v106, v107
	v_pk_mul_f32 v[106:107], v[108:109], v[116:117]
	s_nop 0
	v_sub_f32_e32 v131, v106, v107
	v_pk_mul_f32 v[106:107], v[108:109], v[124:125]
	s_nop 0
	v_add_f32_e32 v109, v106, v107
	v_cvt_pk_bf16_f32 v106, v0, v126
	v_cvt_pk_bf16_f32 v107, v127, v128
	v_cvt_pk_bf16_f32 v108, v129, v130
	v_cvt_pk_bf16_f32 v109, v131, v109
	global_store_dwordx4 v[120:121], v[106:109], off
	s_nop 1
	v_pk_mul_f32 v[106:107], v[102:103], v[160:161]
	v_pk_mul_f32 v[102:103], v[102:103], v[122:123]
	v_sub_f32_e32 v0, v106, v107
	v_add_f32_e32 v106, v102, v103
	v_pk_mul_f32 v[102:103], v[104:105], v[114:115]
	s_nop 0
	v_sub_f32_e32 v107, v102, v103
	v_pk_mul_f32 v[102:103], v[104:105], v[110:111]
	s_nop 0
	v_add_f32_e32 v104, v102, v103
	v_pk_mul_f32 v[102:103], v[98:99], v[118:119]
	v_pk_mul_f32 v[98:99], v[98:99], v[112:113]
	v_sub_f32_e32 v102, v102, v103
	v_add_f32_e32 v103, v98, v99
	v_pk_mul_f32 v[98:99], v[100:101], v[116:117]
	s_nop 0
	v_sub_f32_e32 v105, v98, v99
	v_pk_mul_f32 v[98:99], v[100:101], v[124:125]
	s_nop 0
	v_add_f32_e32 v101, v98, v99
	v_cvt_pk_bf16_f32 v98, v0, v106
	v_cvt_pk_bf16_f32 v99, v107, v104
	v_cvt_pk_bf16_f32 v100, v102, v103
	v_cvt_pk_bf16_f32 v101, v105, v101
	global_store_dwordx4 v[120:121], v[98:101], off offset:256
	v_or_b32_e32 v108, 32, v170
	v_mov_b32_e32 v102, 1.0
	v_mov_b32_e32 v103, 0
	s_and_b64 vcc, exec, s[8:9]
	v_mov_b32_e32 v107, 0
	v_mov_b32_e32 v99, 0
	v_mov_b32_e32 v105, 0
	v_mov_b32_e32 v101, 0
	v_mov_b32_e32 v106, 1.0
	v_mov_b32_e32 v98, 1.0
	v_mov_b32_e32 v104, 1.0
	v_mov_b32_e32 v100, 1.0
	s_cbranch_vccnz .LBB0_149
	v_add_u32_e32 v244, 0xa0, v170
	v_lshlrev_b32_e32 v244, 8, v244
	v_and_b32_e32 v244, 0x7ff00, v244
	v_lshl_add_u64 v[246:247], v[142:143], 0, v[244:245]
	global_load_dwordx4 v[184:187], v[246:247], off
	v_lshl_add_u64 v[246:247], v[144:145], 0, v[244:245]
	global_load_dwordx4 v[188:191], v[246:247], off
	v_add_u32_e32 v244, 0xb0, v170
	v_lshlrev_b32_e32 v244, 8, v244
	v_and_b32_e32 v244, 0x7ff00, v244
	v_lshl_add_u64 v[246:247], v[142:143], 0, v[244:245]
	global_load_dwordx4 v[192:195], v[246:247], off
	v_lshl_add_u64 v[246:247], v[144:145], 0, v[244:245]
	global_load_dwordx4 v[196:199], v[246:247], off
	s_waitcnt vmcnt(14)
	v_mov_b32_e32 v98, v200
	v_mov_b32_e32 v99, v201
	v_mov_b32_e32 v100, v202
	v_mov_b32_e32 v101, v203
	v_mov_b32_e32 v110, v216
	v_mov_b32_e32 v111, v217
	v_mov_b32_e32 v112, v218
	v_mov_b32_e32 v113, v219
	v_mov_b32_e32 v107, v98
	v_mov_b32_e32 v105, v100
	v_mov_b32_e32 v106, v110
	v_mov_b32_e32 v98, v111
	v_mov_b32_e32 v104, v112
	v_mov_b32_e32 v100, v113
.LBB0_149:
	v_mov_b64_e32 v[110:111], s[12:13]
	v_mad_i64_i32 v[108:109], s[0:1], v108, s43, v[110:111]
	v_pk_mul_f32 v[110:111], v[94:95], v[106:107]
	v_mov_b32_e32 v112, v101
	v_sub_f32_e32 v0, v110, v111
	v_mov_b32_e32 v110, v107
	v_mov_b32_e32 v111, v106
	v_pk_mul_f32 v[94:95], v[94:95], v[110:111]
	v_mov_b32_e32 v113, v100
	v_add_f32_e32 v114, v94, v95
	v_pk_mul_f32 v[94:95], v[96:97], v[98:99]
	v_lshl_add_u64 v[108:109], v[158:159], 1, v[108:109]
	v_sub_f32_e32 v115, v94, v95
	v_mov_b32_e32 v94, v99
	v_mov_b32_e32 v95, v98
	v_pk_mul_f32 v[96:97], v[96:97], v[94:95]
	s_nop 0
	v_add_f32_e32 v116, v96, v97
	v_pk_mul_f32 v[96:97], v[90:91], v[104:105]
	s_nop 0
	v_sub_f32_e32 v117, v96, v97
	v_mov_b32_e32 v96, v105
	v_mov_b32_e32 v97, v104
	v_pk_mul_f32 v[90:91], v[90:91], v[96:97]
	s_nop 0
	v_add_f32_e32 v118, v90, v91
	v_pk_mul_f32 v[90:91], v[92:93], v[100:101]
	s_nop 0
	v_sub_f32_e32 v119, v90, v91
	v_pk_mul_f32 v[90:91], v[92:93], v[112:113]
	s_nop 0
	v_add_f32_e32 v93, v90, v91
	v_cvt_pk_bf16_f32 v90, v0, v114
	v_cvt_pk_bf16_f32 v91, v115, v116
	v_cvt_pk_bf16_f32 v92, v117, v118
	v_cvt_pk_bf16_f32 v93, v119, v93
	global_store_dwordx4 v[108:109], v[90:93], off
	s_nop 1
	v_pk_mul_f32 v[90:91], v[86:87], v[106:107]
	v_pk_mul_f32 v[86:87], v[86:87], v[110:111]
	v_sub_f32_e32 v0, v90, v91
	v_add_f32_e32 v90, v86, v87
	v_pk_mul_f32 v[86:87], v[88:89], v[98:99]
	s_nop 0
	v_sub_f32_e32 v91, v86, v87
	v_pk_mul_f32 v[86:87], v[88:89], v[94:95]
	s_nop 0
	v_add_f32_e32 v88, v86, v87
	v_pk_mul_f32 v[86:87], v[82:83], v[104:105]
	v_pk_mul_f32 v[82:83], v[82:83], v[96:97]
	v_sub_f32_e32 v86, v86, v87
	v_add_f32_e32 v87, v82, v83
	v_pk_mul_f32 v[82:83], v[84:85], v[100:101]
	s_nop 0
	v_sub_f32_e32 v89, v82, v83
	v_pk_mul_f32 v[82:83], v[84:85], v[112:113]
	s_nop 0
	v_add_f32_e32 v85, v82, v83
	v_cvt_pk_bf16_f32 v82, v0, v90
	v_cvt_pk_bf16_f32 v83, v91, v88
	v_cvt_pk_bf16_f32 v84, v86, v87
	v_cvt_pk_bf16_f32 v85, v89, v85
	global_store_dwordx4 v[108:109], v[82:85], off offset:256
	v_or_b32_e32 v88, 48, v170
	s_and_b64 vcc, exec, s[8:9]
	v_mov_b32_e32 v83, 0
	v_mov_b32_e32 v87, 0
	v_mov_b32_e32 v85, 0
	v_mov_b32_e32 v82, 1.0
	v_mov_b32_e32 v86, 1.0
	v_mov_b32_e32 v84, 1.0
	s_cbranch_vccnz .LBB0_151
	s_waitcnt vmcnt(14)
	v_mov_b32_e32 v82, v220
	v_mov_b32_e32 v83, v221
	v_mov_b32_e32 v84, v222
	v_mov_b32_e32 v85, v223
	v_mov_b32_e32 v90, v224
	v_mov_b32_e32 v91, v225
	v_mov_b32_e32 v92, v226
	v_mov_b32_e32 v93, v227
	v_mov_b32_e32 v103, v82
	v_mov_b32_e32 v87, v84
	v_mov_b32_e32 v102, v90
	v_mov_b32_e32 v82, v91
	v_mov_b32_e32 v86, v92
	v_mov_b32_e32 v84, v93
.LBB0_151:
	v_mov_b64_e32 v[90:91], s[12:13]
	v_mad_i64_i32 v[88:89], s[0:1], v88, s43, v[90:91]
	v_pk_mul_f32 v[90:91], v[78:79], v[102:103]
	v_mov_b32_e32 v92, v85
	v_sub_f32_e32 v0, v90, v91
	v_mov_b32_e32 v90, v103
	v_mov_b32_e32 v91, v102
	v_pk_mul_f32 v[78:79], v[78:79], v[90:91]
	v_mov_b32_e32 v93, v84
	v_add_f32_e32 v94, v78, v79
	v_pk_mul_f32 v[78:79], v[80:81], v[82:83]
	v_lshl_add_u64 v[88:89], v[158:159], 1, v[88:89]
	v_sub_f32_e32 v95, v78, v79
	v_mov_b32_e32 v78, v83
	v_mov_b32_e32 v79, v82
	v_pk_mul_f32 v[80:81], v[80:81], v[78:79]
	s_nop 0
	v_add_f32_e32 v96, v80, v81
	v_pk_mul_f32 v[80:81], v[74:75], v[86:87]
	s_nop 0
	v_sub_f32_e32 v97, v80, v81
	v_mov_b32_e32 v80, v87
	v_mov_b32_e32 v81, v86
	v_pk_mul_f32 v[74:75], v[74:75], v[80:81]
	s_nop 0
	v_add_f32_e32 v98, v74, v75
	v_pk_mul_f32 v[74:75], v[76:77], v[84:85]
	s_nop 0
	v_sub_f32_e32 v99, v74, v75
	v_pk_mul_f32 v[74:75], v[76:77], v[92:93]
	s_nop 0
	v_add_f32_e32 v77, v74, v75
	v_cvt_pk_bf16_f32 v74, v0, v94
	v_cvt_pk_bf16_f32 v75, v95, v96
	v_cvt_pk_bf16_f32 v76, v97, v98
	v_cvt_pk_bf16_f32 v77, v99, v77
	global_store_dwordx4 v[88:89], v[74:77], off
	s_nop 1
	v_pk_mul_f32 v[74:75], v[70:71], v[102:103]
	v_pk_mul_f32 v[70:71], v[70:71], v[90:91]
	v_sub_f32_e32 v0, v74, v75
	v_add_f32_e32 v74, v70, v71
	v_pk_mul_f32 v[70:71], v[72:73], v[82:83]
	s_nop 0
	v_sub_f32_e32 v75, v70, v71
	v_pk_mul_f32 v[70:71], v[72:73], v[78:79]
	s_nop 0
	v_add_f32_e32 v72, v70, v71
	v_pk_mul_f32 v[70:71], v[66:67], v[86:87]
	v_pk_mul_f32 v[66:67], v[66:67], v[80:81]
	v_sub_f32_e32 v70, v70, v71
	v_add_f32_e32 v71, v66, v67
	v_pk_mul_f32 v[66:67], v[68:69], v[84:85]
	s_nop 0
	v_sub_f32_e32 v73, v66, v67
	v_pk_mul_f32 v[66:67], v[68:69], v[92:93]
	s_nop 0
	v_add_f32_e32 v69, v66, v67
	v_cvt_pk_bf16_f32 v66, v0, v74
	v_cvt_pk_bf16_f32 v67, v75, v72
	v_cvt_pk_bf16_f32 v68, v70, v71
	v_cvt_pk_bf16_f32 v69, v73, v69
	global_store_dwordx4 v[88:89], v[66:69], off offset:256
	v_add_u32_e32 v76, 0x80, v170
	v_mov_b32_e32 v70, 1.0
	v_mov_b32_e32 v71, 0
	s_and_b64 vcc, exec, s[8:9]
	v_mov_b32_e32 v75, 0
	v_mov_b32_e32 v67, 0
	v_mov_b32_e32 v73, 0
	v_mov_b32_e32 v69, 0
	v_mov_b32_e32 v74, 1.0
	v_mov_b32_e32 v66, 1.0
	v_mov_b32_e32 v72, 1.0
	v_mov_b32_e32 v68, 1.0
	s_cbranch_vccnz .LBB0_153
	s_waitcnt vmcnt(14)
	v_mov_b32_e32 v66, v228
	v_mov_b32_e32 v67, v229
	v_mov_b32_e32 v68, v230
	v_mov_b32_e32 v69, v231
	v_mov_b32_e32 v78, v232
	v_mov_b32_e32 v79, v233
	v_mov_b32_e32 v80, v234
	v_mov_b32_e32 v81, v235
	v_mov_b32_e32 v75, v66
	v_mov_b32_e32 v73, v68
	v_mov_b32_e32 v74, v78
	v_mov_b32_e32 v66, v79
	v_mov_b32_e32 v72, v80
	v_mov_b32_e32 v68, v81
.LBB0_153:
	v_mov_b64_e32 v[78:79], s[12:13]
	v_mad_i64_i32 v[76:77], s[0:1], v76, s43, v[78:79]
	v_pk_mul_f32 v[78:79], v[62:63], v[74:75]
	v_mov_b32_e32 v80, v69
	v_sub_f32_e32 v0, v78, v79
	v_mov_b32_e32 v78, v75
	v_mov_b32_e32 v79, v74
	v_pk_mul_f32 v[62:63], v[62:63], v[78:79]
	v_mov_b32_e32 v81, v68
	v_add_f32_e32 v82, v62, v63
	v_pk_mul_f32 v[62:63], v[64:65], v[66:67]
	v_lshl_add_u64 v[76:77], v[158:159], 1, v[76:77]
	v_sub_f32_e32 v83, v62, v63
	v_mov_b32_e32 v62, v67
	v_mov_b32_e32 v63, v66
	v_pk_mul_f32 v[64:65], v[64:65], v[62:63]
	s_nop 0
	v_add_f32_e32 v84, v64, v65
	v_pk_mul_f32 v[64:65], v[58:59], v[72:73]
	s_nop 0
	v_sub_f32_e32 v85, v64, v65
	v_mov_b32_e32 v64, v73
	v_mov_b32_e32 v65, v72
	v_pk_mul_f32 v[58:59], v[58:59], v[64:65]
	s_nop 0
	v_add_f32_e32 v86, v58, v59
	v_pk_mul_f32 v[58:59], v[60:61], v[68:69]
	s_nop 0
	v_sub_f32_e32 v87, v58, v59
	v_pk_mul_f32 v[58:59], v[60:61], v[80:81]
	s_nop 0
	v_add_f32_e32 v61, v58, v59
	v_cvt_pk_bf16_f32 v58, v0, v82
	v_cvt_pk_bf16_f32 v59, v83, v84
	v_cvt_pk_bf16_f32 v60, v85, v86
	v_cvt_pk_bf16_f32 v61, v87, v61
	global_store_dwordx4 v[76:77], v[58:61], off
	s_nop 1
	v_pk_mul_f32 v[58:59], v[54:55], v[74:75]
	v_pk_mul_f32 v[54:55], v[54:55], v[78:79]
	v_sub_f32_e32 v0, v58, v59
	v_add_f32_e32 v58, v54, v55
	v_pk_mul_f32 v[54:55], v[56:57], v[66:67]
	s_nop 0
	v_sub_f32_e32 v59, v54, v55
	v_pk_mul_f32 v[54:55], v[56:57], v[62:63]
	s_nop 0
	v_add_f32_e32 v56, v54, v55
	v_pk_mul_f32 v[54:55], v[50:51], v[72:73]
	v_pk_mul_f32 v[50:51], v[50:51], v[64:65]
	v_sub_f32_e32 v54, v54, v55
	v_add_f32_e32 v55, v50, v51
	v_pk_mul_f32 v[50:51], v[52:53], v[68:69]
	s_nop 0
	v_sub_f32_e32 v57, v50, v51
	v_pk_mul_f32 v[50:51], v[52:53], v[80:81]
	s_nop 0
	v_add_f32_e32 v53, v50, v51
	v_cvt_pk_bf16_f32 v50, v0, v58
	v_cvt_pk_bf16_f32 v51, v59, v56
	v_cvt_pk_bf16_f32 v52, v54, v55
	v_cvt_pk_bf16_f32 v53, v57, v53
	global_store_dwordx4 v[76:77], v[50:53], off offset:256
	v_add_u32_e32 v56, 0x90, v170
	s_and_b64 vcc, exec, s[8:9]
	v_mov_b32_e32 v51, 0
	v_mov_b32_e32 v55, 0
	v_mov_b32_e32 v53, 0
	v_mov_b32_e32 v50, 1.0
	v_mov_b32_e32 v54, 1.0
	v_mov_b32_e32 v52, 1.0
	s_cbranch_vccnz .LBB0_155
	s_waitcnt vmcnt(14)
	v_mov_b32_e32 v50, v236
	v_mov_b32_e32 v51, v237
	v_mov_b32_e32 v52, v238
	v_mov_b32_e32 v53, v239
	v_mov_b32_e32 v58, v240
	v_mov_b32_e32 v59, v241
	v_mov_b32_e32 v60, v242
	v_mov_b32_e32 v61, v243
	v_mov_b32_e32 v71, v50
	v_mov_b32_e32 v55, v52
	v_mov_b32_e32 v70, v58
	v_mov_b32_e32 v50, v59
	v_mov_b32_e32 v54, v60
	v_mov_b32_e32 v52, v61
.LBB0_155:
	v_mov_b64_e32 v[58:59], s[12:13]
	v_mad_i64_i32 v[56:57], s[0:1], v56, s43, v[58:59]
	v_pk_mul_f32 v[58:59], v[46:47], v[70:71]
	v_mov_b32_e32 v60, v53
	v_sub_f32_e32 v0, v58, v59
	v_mov_b32_e32 v58, v71
	v_mov_b32_e32 v59, v70
	v_pk_mul_f32 v[46:47], v[46:47], v[58:59]
	v_mov_b32_e32 v61, v52
	v_add_f32_e32 v62, v46, v47
	v_pk_mul_f32 v[46:47], v[48:49], v[50:51]
	v_lshl_add_u64 v[56:57], v[158:159], 1, v[56:57]
	v_sub_f32_e32 v63, v46, v47
	v_mov_b32_e32 v46, v51
	v_mov_b32_e32 v47, v50
	v_pk_mul_f32 v[48:49], v[48:49], v[46:47]
	s_nop 0
	v_add_f32_e32 v64, v48, v49
	v_pk_mul_f32 v[48:49], v[42:43], v[54:55]
	s_nop 0
	v_sub_f32_e32 v65, v48, v49
	v_mov_b32_e32 v48, v55
	v_mov_b32_e32 v49, v54
	v_pk_mul_f32 v[42:43], v[42:43], v[48:49]
	s_nop 0
	v_add_f32_e32 v66, v42, v43
	v_pk_mul_f32 v[42:43], v[44:45], v[52:53]
	s_nop 0
	v_sub_f32_e32 v67, v42, v43
	v_pk_mul_f32 v[42:43], v[44:45], v[60:61]
	s_nop 0
	v_add_f32_e32 v45, v42, v43
	v_cvt_pk_bf16_f32 v42, v0, v62
	v_cvt_pk_bf16_f32 v43, v63, v64
	v_cvt_pk_bf16_f32 v44, v65, v66
	v_cvt_pk_bf16_f32 v45, v67, v45
	global_store_dwordx4 v[56:57], v[42:45], off
	s_nop 1
	v_pk_mul_f32 v[42:43], v[38:39], v[70:71]
	v_pk_mul_f32 v[38:39], v[38:39], v[58:59]
	v_sub_f32_e32 v0, v42, v43
	v_add_f32_e32 v42, v38, v39
	v_pk_mul_f32 v[38:39], v[40:41], v[50:51]
	s_nop 0
	v_sub_f32_e32 v43, v38, v39
	v_pk_mul_f32 v[38:39], v[40:41], v[46:47]
	s_nop 0
	v_add_f32_e32 v40, v38, v39
	v_pk_mul_f32 v[38:39], v[34:35], v[54:55]
	v_pk_mul_f32 v[34:35], v[34:35], v[48:49]
	v_sub_f32_e32 v38, v38, v39
	v_add_f32_e32 v39, v34, v35
	v_pk_mul_f32 v[34:35], v[36:37], v[52:53]
	s_nop 0
	v_sub_f32_e32 v41, v34, v35
	v_pk_mul_f32 v[34:35], v[36:37], v[60:61]
	s_nop 0
	v_add_f32_e32 v37, v34, v35
	v_cvt_pk_bf16_f32 v34, v0, v42
	v_cvt_pk_bf16_f32 v35, v43, v40
	v_cvt_pk_bf16_f32 v36, v38, v39
	v_cvt_pk_bf16_f32 v37, v41, v37
	global_store_dwordx4 v[56:57], v[34:37], off offset:256
	v_add_u32_e32 v44, 0xa0, v170
	v_mov_b32_e32 v38, 1.0
	v_mov_b32_e32 v39, 0
	s_and_b64 vcc, exec, s[8:9]
	v_mov_b32_e32 v43, 0
	v_mov_b32_e32 v35, 0
	v_mov_b32_e32 v41, 0
	v_mov_b32_e32 v37, 0
	v_mov_b32_e32 v42, 1.0
	v_mov_b32_e32 v34, 1.0
	v_mov_b32_e32 v40, 1.0
	v_mov_b32_e32 v36, 1.0
	s_cbranch_vccnz .LBB0_157
	s_waitcnt vmcnt(10)
	v_mov_b32_e32 v34, v184
	v_mov_b32_e32 v35, v185
	v_mov_b32_e32 v36, v186
	v_mov_b32_e32 v37, v187
	v_mov_b32_e32 v46, v188
	v_mov_b32_e32 v47, v189
	v_mov_b32_e32 v48, v190
	v_mov_b32_e32 v49, v191
	v_mov_b32_e32 v43, v34
	v_mov_b32_e32 v41, v36
	v_mov_b32_e32 v42, v46
	v_mov_b32_e32 v34, v47
	v_mov_b32_e32 v40, v48
	v_mov_b32_e32 v36, v49
.LBB0_157:
	v_mov_b64_e32 v[46:47], s[12:13]
	v_mad_i64_i32 v[44:45], s[0:1], v44, s43, v[46:47]
	v_pk_mul_f32 v[46:47], v[30:31], v[42:43]
	v_mov_b32_e32 v48, v37
	v_sub_f32_e32 v0, v46, v47
	v_mov_b32_e32 v46, v43
	v_mov_b32_e32 v47, v42
	v_pk_mul_f32 v[30:31], v[30:31], v[46:47]
	v_mov_b32_e32 v49, v36
	v_add_f32_e32 v50, v30, v31
	v_pk_mul_f32 v[30:31], v[32:33], v[34:35]
	v_lshl_add_u64 v[44:45], v[158:159], 1, v[44:45]
	v_sub_f32_e32 v51, v30, v31
	v_mov_b32_e32 v30, v35
	v_mov_b32_e32 v31, v34
	v_pk_mul_f32 v[32:33], v[32:33], v[30:31]
	s_nop 0
	v_add_f32_e32 v52, v32, v33
	v_pk_mul_f32 v[32:33], v[26:27], v[40:41]
	s_nop 0
	v_sub_f32_e32 v53, v32, v33
	v_mov_b32_e32 v32, v41
	v_mov_b32_e32 v33, v40
	v_pk_mul_f32 v[26:27], v[26:27], v[32:33]
	s_nop 0
	v_add_f32_e32 v54, v26, v27
	v_pk_mul_f32 v[26:27], v[28:29], v[36:37]
	s_nop 0
	v_sub_f32_e32 v55, v26, v27
	v_pk_mul_f32 v[26:27], v[28:29], v[48:49]
	s_nop 0
	v_add_f32_e32 v29, v26, v27
	v_cvt_pk_bf16_f32 v26, v0, v50
	v_cvt_pk_bf16_f32 v27, v51, v52
	v_cvt_pk_bf16_f32 v28, v53, v54
	v_cvt_pk_bf16_f32 v29, v55, v29
	global_store_dwordx4 v[44:45], v[26:29], off
	s_nop 1
	v_pk_mul_f32 v[26:27], v[22:23], v[42:43]
	v_pk_mul_f32 v[22:23], v[22:23], v[46:47]
	v_sub_f32_e32 v0, v26, v27
	v_add_f32_e32 v26, v22, v23
	v_pk_mul_f32 v[22:23], v[24:25], v[34:35]
	s_nop 0
	v_sub_f32_e32 v27, v22, v23
	v_pk_mul_f32 v[22:23], v[24:25], v[30:31]
	s_nop 0
	v_add_f32_e32 v24, v22, v23
	v_pk_mul_f32 v[22:23], v[18:19], v[40:41]
	v_pk_mul_f32 v[18:19], v[18:19], v[32:33]
	v_sub_f32_e32 v22, v22, v23
	v_add_f32_e32 v23, v18, v19
	v_pk_mul_f32 v[18:19], v[20:21], v[36:37]
	s_nop 0
	v_sub_f32_e32 v25, v18, v19
	v_pk_mul_f32 v[18:19], v[20:21], v[48:49]
	s_nop 0
	v_add_f32_e32 v21, v18, v19
	v_cvt_pk_bf16_f32 v18, v0, v26
	v_cvt_pk_bf16_f32 v19, v27, v24
	v_cvt_pk_bf16_f32 v20, v22, v23
	v_cvt_pk_bf16_f32 v21, v25, v21
	global_store_dwordx4 v[44:45], v[18:21], off offset:256
	v_add_u32_e32 v24, 0xb0, v170
	s_and_b64 vcc, exec, s[8:9]
	v_mov_b32_e32 v19, 0
	v_mov_b32_e32 v23, 0
	v_mov_b32_e32 v21, 0
	v_mov_b32_e32 v18, 1.0
	v_mov_b32_e32 v22, 1.0
	v_mov_b32_e32 v20, 1.0
	s_cbranch_vccnz .LBB0_159
	s_waitcnt vmcnt(10)
	v_mov_b32_e32 v18, v192
	v_mov_b32_e32 v19, v193
	v_mov_b32_e32 v20, v194
	v_mov_b32_e32 v21, v195
	v_mov_b32_e32 v26, v196
	v_mov_b32_e32 v27, v197
	v_mov_b32_e32 v28, v198
	v_mov_b32_e32 v29, v199
	v_mov_b32_e32 v39, v18
	v_mov_b32_e32 v23, v20
	v_mov_b32_e32 v38, v26
	v_mov_b32_e32 v18, v27
	v_mov_b32_e32 v22, v28
	v_mov_b32_e32 v20, v29
.LBB0_159:
	v_mov_b64_e32 v[26:27], s[12:13]
	v_mad_i64_i32 v[24:25], s[0:1], v24, s43, v[26:27]
	v_pk_mul_f32 v[26:27], v[14:15], v[38:39]
	v_mov_b32_e32 v28, v21
	v_sub_f32_e32 v0, v26, v27
	v_mov_b32_e32 v26, v39
	v_mov_b32_e32 v27, v38
	v_pk_mul_f32 v[14:15], v[14:15], v[26:27]
	v_mov_b32_e32 v29, v20
	v_add_f32_e32 v30, v14, v15
	v_pk_mul_f32 v[14:15], v[16:17], v[18:19]
	v_lshl_add_u64 v[24:25], v[158:159], 1, v[24:25]
	v_sub_f32_e32 v31, v14, v15
	v_mov_b32_e32 v14, v19
	v_mov_b32_e32 v15, v18
	v_pk_mul_f32 v[16:17], v[16:17], v[14:15]
	s_nop 0
	v_add_f32_e32 v32, v16, v17
	v_pk_mul_f32 v[16:17], v[10:11], v[22:23]
	s_nop 0
	v_sub_f32_e32 v33, v16, v17
	v_mov_b32_e32 v16, v23
	v_mov_b32_e32 v17, v22
	v_pk_mul_f32 v[10:11], v[10:11], v[16:17]
	s_nop 0
	v_add_f32_e32 v34, v10, v11
	v_pk_mul_f32 v[10:11], v[12:13], v[20:21]
	s_nop 0
	v_sub_f32_e32 v35, v10, v11
	v_pk_mul_f32 v[10:11], v[12:13], v[28:29]
	s_nop 0
	v_add_f32_e32 v13, v10, v11
	v_cvt_pk_bf16_f32 v10, v0, v30
	v_cvt_pk_bf16_f32 v11, v31, v32
	v_cvt_pk_bf16_f32 v12, v33, v34
	v_cvt_pk_bf16_f32 v13, v35, v13
	global_store_dwordx4 v[24:25], v[10:13], off
	s_nop 1
	v_pk_mul_f32 v[10:11], v[6:7], v[38:39]
	v_pk_mul_f32 v[6:7], v[6:7], v[26:27]
	v_sub_f32_e32 v0, v10, v11
	v_add_f32_e32 v10, v6, v7
	v_pk_mul_f32 v[6:7], v[8:9], v[18:19]
	s_nop 0
	v_sub_f32_e32 v11, v6, v7
	v_pk_mul_f32 v[6:7], v[8:9], v[14:15]
	s_nop 0
	v_add_f32_e32 v8, v6, v7
	v_pk_mul_f32 v[6:7], v[2:3], v[22:23]
	v_pk_mul_f32 v[2:3], v[2:3], v[16:17]
	v_sub_f32_e32 v6, v6, v7
	v_add_f32_e32 v7, v2, v3
	v_pk_mul_f32 v[2:3], v[4:5], v[20:21]
	s_nop 0
	v_sub_f32_e32 v9, v2, v3
	v_pk_mul_f32 v[2:3], v[4:5], v[28:29]
	s_nop 0
	v_add_f32_e32 v5, v2, v3
	v_cvt_pk_bf16_f32 v2, v0, v10
	v_cvt_pk_bf16_f32 v3, v11, v8
	v_cvt_pk_bf16_f32 v4, v6, v7
	v_cvt_pk_bf16_f32 v5, v9, v5
	global_store_dwordx4 v[24:25], v[2:5], off offset:256
	s_andn2_b64 vcc, exec, s[6:7]
	s_mov_b64 s[0:1], -1
	s_cbranch_vccnz .LBB0_136
	s_andn2_b64 vcc, exec, s[4:5]
	s_cbranch_vccnz .LBB0_135
	s_barrier
	s_branch .LBB0_135
